# v21
# baseline (speedup 1.0000x reference)
; __device__ __forceinline__ float sigm(float x) { return __builtin_amdgcn_rcpf(1.f + __builtin_amdgcn_exp2f(-1.4426950409f * x)); }
; __device__ __forceinline__ u32x4 pack8(const f32x4 v0, const f32x4 v1) { u32x4 w; w.x = cvt_pk_bf16(v0[0], v0[1]); w.y = cvt_pk_bf16(v0[2], v0[3]); w.z = cvt_pk_bf16(v1[0], v1[1]); w.w = cvt_pk_bf16(v1[2], v1[3]); return w; }
; __device__ __forceinline__ void unpack8(const u32x4 w, f32x4& lo, f32x4& hi) { lo = (f32x4){bf_lo(w.x), bf_hi(w.x), bf_lo(w.y), bf_hi(w.y)}; hi = (f32x4){bf_lo(w.z), bf_hi(w.z), bf_lo(w.w), bf_hi(w.w)}; }
;     __device__ __forceinline__ void operator()(AccT& acc, const Unit& u, int wr, int wc, int fr, int fq) const {
;     ...
;         if (u.kind == 0) {
; #pragma unroll
;             for (int bj = 0; bj < 2; ++bj) { const f32x4 b0 = *(const f32x4*)(glu_b + col0 + bj * 128), b1 = *(const f32x4*)(glu_b + col0 + bj * 128 + 4);
; #pragma unroll
;                 for (int ai = 0; ai < 2; ++ai)
; #pragma unroll
;                     for (int m = 0; m < 4; ++m) { const size_t off = (size_t)(row0 + ai * 128 + m * 16) * DSS + col0 + bj * 128;
;                         f32x4 y0, y1; unpack8(*(const u32x4*)(YG + off), y0, y1);
;                         f32x4 v0 = acc[ai][bj][m][0] + b0, v1 = acc[ai][bj][m][1] + b1;
; #pragma unroll
;                         for (int j = 0; j < 4; ++j) { v0[j] = y0[j] * sigm(v0[j]); v1[j] = y1[j] * sigm(v1[j]); }
;                         *(u32x4*)(YS + off) = pack8(v0, v1); } }
.LBB0_413:
	v_lshl_add_u64 v[140:141], v[148:149], 2, s[44:45]
	global_load_dwordx4 v[108:111], v[140:141], off
	global_load_dwordx4 v[104:107], v[140:141], off offset:16
	v_lshlrev_b64 v[150:151], 11, v[150:151]
	v_lshl_add_u64 v[136:137], v[150:151], 0, v[148:149]
	v_lshlrev_b64 v[158:159], 1, v[136:137]
	v_lshl_add_u64 v[136:137], s[14:15], 0, v[158:159]
	global_load_dwordx4 v[186:189], v[136:137], off
	global_load_dwordx4 v[218:221], v[136:137], off offset:256
	s_mov_b64 s[4:5], 0x10000
	v_lshl_add_u64 v[166:167], v[136:137], 0, s[4:5]
	global_load_dwordx4 v[190:193], v[166:167], off
	global_load_dwordx4 v[222:225], v[166:167], off offset:256
	s_mov_b64 s[4:5], 0x20000
	v_lshl_add_u64 v[166:167], v[136:137], 0, s[4:5]
	global_load_dwordx4 v[194:197], v[166:167], off
	global_load_dwordx4 v[226:229], v[166:167], off offset:256
	s_mov_b64 s[4:5], 0x30000
	v_lshl_add_u64 v[166:167], v[136:137], 0, s[4:5]
	global_load_dwordx4 v[198:201], v[166:167], off
	global_load_dwordx4 v[230:233], v[166:167], off offset:256
	s_mov_b64 s[4:5], 0x80000
	v_lshl_add_u64 v[166:167], v[136:137], 0, s[4:5]
	global_load_dwordx4 v[202:205], v[166:167], off
	global_load_dwordx4 v[234:237], v[166:167], off offset:256
	s_mov_b64 s[4:5], 0x90000
	v_lshl_add_u64 v[166:167], v[136:137], 0, s[4:5]
	global_load_dwordx4 v[206:209], v[166:167], off
	global_load_dwordx4 v[238:241], v[166:167], off offset:256
	s_mov_b64 s[4:5], 0xa0000
	v_lshl_add_u64 v[166:167], v[136:137], 0, s[4:5]
	global_load_dwordx4 v[210:213], v[166:167], off
	global_load_dwordx4 v[242:245], v[166:167], off offset:256
	s_mov_b64 s[4:5], 0xb0000
	v_lshl_add_u64 v[166:167], v[136:137], 0, s[4:5]
	global_load_dwordx4 v[214:217], v[166:167], off
	global_load_dwordx4 v[246:249], v[166:167], off offset:256
	v_lshlrev_b64 v[142:143], 11, v[156:157]
	v_lshl_add_u64 v[156:157], v[142:143], 0, v[148:149]
	v_lshlrev_b64 v[156:157], 1, v[156:157]
	v_lshl_add_u64 v[158:159], s[26:27], 0, v[158:159]
	v_lshl_add_u64 v[160:161], s[14:15], 0, v[156:157]
	s_mov_b64 s[4:5], 0x40000
	s_waitcnt vmcnt(2)
	v_pk_add_f32 v[134:135], v[134:135], v[110:111]
	v_pk_add_f32 v[132:133], v[132:133], v[108:109]
	s_waitcnt vmcnt(1)
	v_pk_add_f32 v[130:131], v[130:131], v[106:107]
	v_pk_add_f32 v[128:129], v[128:129], v[104:105]
	v_mul_f32_e32 v132, 0xbfb8aa3b, v132
	v_mul_f32_e32 v128, 0xbfb8aa3b, v128
	v_mul_f32_e32 v133, 0xbfb8aa3b, v133
	v_mul_f32_e32 v129, 0xbfb8aa3b, v129
	v_mul_f32_e32 v134, 0xbfb8aa3b, v134
	v_mul_f32_e32 v130, 0xbfb8aa3b, v130
	v_mul_f32_e32 v135, 0xbfb8aa3b, v135
	v_mul_f32_e32 v131, 0xbfb8aa3b, v131
	v_exp_f32_e32 v132, v132
	v_exp_f32_e32 v128, v128
	v_exp_f32_e32 v133, v133
	v_exp_f32_e32 v129, v129
	v_exp_f32_e32 v134, v134
	v_exp_f32_e32 v130, v130
	v_exp_f32_e32 v135, v135
	v_exp_f32_e32 v131, v131
	v_add_f32_e32 v132, 1.0, v132
	v_add_f32_e32 v128, 1.0, v128
	v_add_f32_e32 v133, 1.0, v133
	v_add_f32_e32 v129, 1.0, v129
	v_add_f32_e32 v134, 1.0, v134
	v_add_f32_e32 v130, 1.0, v130
	v_add_f32_e32 v135, 1.0, v135
	v_add_f32_e32 v131, 1.0, v131
	v_rcp_f32_e32 v132, v132
	v_rcp_f32_e32 v128, v128
	v_rcp_f32_e32 v133, v133
	v_rcp_f32_e32 v129, v129
	v_rcp_f32_e32 v134, v134
	v_rcp_f32_e32 v130, v130
	v_rcp_f32_e32 v135, v135
	v_rcp_f32_e32 v131, v131
	s_waitcnt vmcnt(0)
	v_mov_b32_e32 v136, v186
	v_mov_b32_e32 v137, v187
	v_mov_b32_e32 v138, v188
	v_mov_b32_e32 v139, v189
	v_lshlrev_b32_e32 v162, 16, v136
	v_and_b32_e32 v136, 0xffff0000, v136
	v_lshlrev_b32_e32 v163, 16, v137
	v_and_b32_e32 v137, 0xffff0000, v137
	v_lshlrev_b32_e32 v164, 16, v138
	v_and_b32_e32 v138, 0xffff0000, v138
	v_lshlrev_b32_e32 v165, 16, v139
	v_and_b32_e32 v139, 0xffff0000, v139
	v_mul_f32_e32 v132, v132, v162
	v_mul_f32_e32 v162, v128, v164
	v_mul_f32_e32 v128, v133, v136
	v_mul_f32_e32 v133, v129, v138
	v_mul_f32_e32 v129, v134, v163
	v_mul_f32_e32 v134, v130, v165
	v_mul_f32_e32 v130, v135, v137
	v_mul_f32_e32 v131, v131, v139
	v_cvt_pk_bf16_f32 v128, v132, v128
	v_cvt_pk_bf16_f32 v129, v129, v130
	v_cvt_pk_bf16_f32 v130, v162, v133
	v_cvt_pk_bf16_f32 v131, v134, v131
	global_store_dwordx4 v[158:159], v[128:131], off
	s_nop 1
	v_mov_b32_e32 v128, v190
	v_mov_b32_e32 v129, v191
	v_mov_b32_e32 v130, v192
	v_mov_b32_e32 v131, v193
	v_pk_add_f32 v[126:127], v[126:127], v[110:111]
	v_pk_add_f32 v[124:125], v[124:125], v[108:109]
	v_pk_add_f32 v[122:123], v[122:123], v[106:107]
	v_pk_add_f32 v[120:121], v[120:121], v[104:105]
	v_mul_f32_e32 v124, 0xbfb8aa3b, v124
	v_mul_f32_e32 v120, 0xbfb8aa3b, v120
	v_mul_f32_e32 v125, 0xbfb8aa3b, v125
	v_mul_f32_e32 v121, 0xbfb8aa3b, v121
	v_mul_f32_e32 v126, 0xbfb8aa3b, v126
	v_mul_f32_e32 v122, 0xbfb8aa3b, v122
	v_mul_f32_e32 v127, 0xbfb8aa3b, v127
	v_mul_f32_e32 v123, 0xbfb8aa3b, v123
	v_exp_f32_e32 v124, v124
	v_exp_f32_e32 v120, v120
	v_exp_f32_e32 v125, v125
	v_exp_f32_e32 v121, v121
	v_exp_f32_e32 v126, v126
	v_exp_f32_e32 v122, v122
	v_exp_f32_e32 v127, v127
	v_exp_f32_e32 v123, v123
	v_add_f32_e32 v124, 1.0, v124
	v_add_f32_e32 v120, 1.0, v120
	v_add_f32_e32 v125, 1.0, v125
	v_add_f32_e32 v121, 1.0, v121
	v_add_f32_e32 v126, 1.0, v126
	v_add_f32_e32 v122, 1.0, v122
	v_add_f32_e32 v127, 1.0, v127
	v_add_f32_e32 v123, 1.0, v123
	v_rcp_f32_e32 v124, v124
	v_rcp_f32_e32 v120, v120
	v_rcp_f32_e32 v125, v125
	v_rcp_f32_e32 v121, v121
	v_rcp_f32_e32 v126, v126
	v_rcp_f32_e32 v122, v122
	v_rcp_f32_e32 v127, v127
	v_rcp_f32_e32 v123, v123
	v_lshlrev_b64 v[132:133], 11, v[154:155]
	v_lshl_add_u64 v[134:135], v[132:133], 0, v[148:149]
	v_lshl_add_u64 v[136:137], s[26:27], 0, v[156:157]
	v_lshlrev_b64 v[134:135], 1, v[134:135]
	v_lshl_add_u64 v[138:139], s[14:15], 0, v[134:135]
; __device__ __forceinline__ float sigm(float x) { return __builtin_amdgcn_rcpf(1.f + __builtin_amdgcn_exp2f(-1.4426950409f * x)); }
; __device__ __forceinline__ u32x4 pack8(const f32x4 v0, const f32x4 v1) { u32x4 w; w.x = cvt_pk_bf16(v0[0], v0[1]); w.y = cvt_pk_bf16(v0[2], v0[3]); w.z = cvt_pk_bf16(v1[0], v1[1]); w.w = cvt_pk_bf16(v1[2], v1[3]); return w; }
; __device__ __forceinline__ void unpack8(const u32x4 w, f32x4& lo, f32x4& hi) { lo = (f32x4){bf_lo(w.x), bf_hi(w.x), bf_lo(w.y), bf_hi(w.y)}; hi = (f32x4){bf_lo(w.z), bf_hi(w.z), bf_lo(w.w), bf_hi(w.w)}; }
;     __device__ __forceinline__ void operator()(AccT& acc, const Unit& u, int wr, int wc, int fr, int fq) const {
;     ...
;                     for (int m = 0; m < 4; ++m) { const size_t off = (size_t)(row0 + ai * 128 + m * 16) * DSS + col0 + bj * 128;
;                         f32x4 y0, y1; unpack8(*(const u32x4*)(YG + off), y0, y1);
;                         f32x4 v0 = acc[ai][bj][m][0] + b0, v1 = acc[ai][bj][m][1] + b1;
; #pragma unroll
;                         for (int j = 0; j < 4; ++j) { v0[j] = y0[j] * sigm(v0[j]); v1[j] = y1[j] * sigm(v1[j]); }
;                         *(u32x4*)(YS + off) = pack8(v0, v1); } }
	v_pk_add_f32 v[118:119], v[118:119], v[110:111]
	v_pk_add_f32 v[116:117], v[116:117], v[108:109]
	v_pk_add_f32 v[114:115], v[114:115], v[106:107]
	v_pk_add_f32 v[112:113], v[112:113], v[104:105]
	v_mul_f32_e32 v116, 0xbfb8aa3b, v116
	v_mul_f32_e32 v112, 0xbfb8aa3b, v112
	v_mul_f32_e32 v117, 0xbfb8aa3b, v117
	v_mul_f32_e32 v113, 0xbfb8aa3b, v113
	v_mul_f32_e32 v118, 0xbfb8aa3b, v118
	v_mul_f32_e32 v114, 0xbfb8aa3b, v114
	v_mul_f32_e32 v119, 0xbfb8aa3b, v119
	v_mul_f32_e32 v115, 0xbfb8aa3b, v115
	v_exp_f32_e32 v116, v116
	v_exp_f32_e32 v112, v112
	v_exp_f32_e32 v117, v117
	v_exp_f32_e32 v113, v113
	v_exp_f32_e32 v118, v118
	v_exp_f32_e32 v114, v114
	v_exp_f32_e32 v119, v119
	v_exp_f32_e32 v115, v115
	v_add_f32_e32 v116, 1.0, v116
	v_add_f32_e32 v112, 1.0, v112
	v_add_f32_e32 v117, 1.0, v117
	v_add_f32_e32 v113, 1.0, v113
	v_add_f32_e32 v118, 1.0, v118
	v_add_f32_e32 v114, 1.0, v114
	v_add_f32_e32 v119, 1.0, v119
	v_add_f32_e32 v115, 1.0, v115
	v_rcp_f32_e32 v116, v116
	v_rcp_f32_e32 v112, v112
	v_rcp_f32_e32 v117, v117
	v_rcp_f32_e32 v113, v113
	v_rcp_f32_e32 v118, v118
	v_rcp_f32_e32 v114, v114
	v_rcp_f32_e32 v119, v119
	v_rcp_f32_e32 v115, v115
	v_pk_add_f32 v[102:103], v[102:103], v[110:111]
	v_pk_add_f32 v[100:101], v[100:101], v[108:109]
	v_lshlrev_b32_e32 v154, 16, v128
	v_and_b32_e32 v128, 0xffff0000, v128
	v_lshlrev_b32_e32 v155, 16, v129
	v_and_b32_e32 v129, 0xffff0000, v129
	v_lshlrev_b32_e32 v156, 16, v130
	v_and_b32_e32 v130, 0xffff0000, v130
	v_lshlrev_b32_e32 v157, 16, v131
	v_and_b32_e32 v131, 0xffff0000, v131
	v_mul_f32_e32 v124, v124, v154
	v_mul_f32_e32 v154, v120, v156
	v_mul_f32_e32 v120, v125, v128
	v_mul_f32_e32 v125, v121, v130
	v_mul_f32_e32 v121, v126, v155
	v_mul_f32_e32 v126, v122, v157
	v_mul_f32_e32 v122, v127, v129
	v_mul_f32_e32 v123, v123, v131
	v_cvt_pk_bf16_f32 v120, v124, v120
	v_cvt_pk_bf16_f32 v121, v121, v122
	v_cvt_pk_bf16_f32 v122, v154, v125
	v_cvt_pk_bf16_f32 v123, v126, v123
	global_store_dwordx4 v[136:137], v[120:123], off
	s_nop 1
	v_mov_b32_e32 v120, v194
	v_mov_b32_e32 v121, v195
	v_mov_b32_e32 v122, v196
	v_mov_b32_e32 v123, v197
	v_lshlrev_b64 v[124:125], 11, v[152:153]
	v_lshl_add_u64 v[126:127], v[124:125], 0, v[148:149]
	v_lshl_add_u64 v[128:129], s[26:27], 0, v[134:135]
	v_lshlrev_b64 v[126:127], 1, v[126:127]
	v_lshl_add_u64 v[130:131], s[14:15], 0, v[126:127]
	v_pk_add_f32 v[98:99], v[98:99], v[106:107]
	v_pk_add_f32 v[96:97], v[96:97], v[104:105]
	v_mul_f32_e32 v100, 0xbfb8aa3b, v100
	v_mul_f32_e32 v96, 0xbfb8aa3b, v96
	v_mul_f32_e32 v101, 0xbfb8aa3b, v101
	v_mul_f32_e32 v97, 0xbfb8aa3b, v97
	v_mul_f32_e32 v102, 0xbfb8aa3b, v102
	v_mul_f32_e32 v98, 0xbfb8aa3b, v98
	v_mul_f32_e32 v103, 0xbfb8aa3b, v103
	v_mul_f32_e32 v99, 0xbfb8aa3b, v99
	v_exp_f32_e32 v100, v100
	v_exp_f32_e32 v96, v96
	v_exp_f32_e32 v101, v101
	v_exp_f32_e32 v97, v97
	v_exp_f32_e32 v102, v102
	v_exp_f32_e32 v98, v98
	v_exp_f32_e32 v103, v103
	v_exp_f32_e32 v99, v99
	v_add_f32_e32 v100, 1.0, v100
	v_add_f32_e32 v96, 1.0, v96
	v_add_f32_e32 v101, 1.0, v101
	v_add_f32_e32 v97, 1.0, v97
	v_add_f32_e32 v102, 1.0, v102
	v_add_f32_e32 v98, 1.0, v98
	v_add_f32_e32 v103, 1.0, v103
	v_add_f32_e32 v99, 1.0, v99
	v_rcp_f32_e32 v100, v100
	v_rcp_f32_e32 v96, v96
	v_rcp_f32_e32 v101, v101
	v_rcp_f32_e32 v97, v97
	v_rcp_f32_e32 v102, v102
	v_rcp_f32_e32 v98, v98
	v_rcp_f32_e32 v103, v103
	v_rcp_f32_e32 v99, v99
	v_pk_add_f32 v[94:95], v[94:95], v[110:111]
	v_pk_add_f32 v[92:93], v[92:93], v[108:109]
	v_pk_add_f32 v[90:91], v[90:91], v[106:107]
	v_pk_add_f32 v[88:89], v[88:89], v[104:105]
	v_mul_f32_e32 v92, 0xbfb8aa3b, v92
	v_mul_f32_e32 v88, 0xbfb8aa3b, v88
	v_mul_f32_e32 v93, 0xbfb8aa3b, v93
	v_mul_f32_e32 v89, 0xbfb8aa3b, v89
	v_mul_f32_e32 v94, 0xbfb8aa3b, v94
	v_mul_f32_e32 v90, 0xbfb8aa3b, v90
	v_mul_f32_e32 v95, 0xbfb8aa3b, v95
	v_mul_f32_e32 v91, 0xbfb8aa3b, v91
	v_exp_f32_e32 v92, v92
	v_exp_f32_e32 v88, v88
	v_exp_f32_e32 v93, v93
	v_exp_f32_e32 v89, v89
	v_exp_f32_e32 v94, v94
	v_exp_f32_e32 v90, v90
	v_exp_f32_e32 v95, v95
	v_exp_f32_e32 v91, v91
	v_add_f32_e32 v92, 1.0, v92
	v_add_f32_e32 v88, 1.0, v88
	v_add_f32_e32 v93, 1.0, v93
	v_add_f32_e32 v89, 1.0, v89
	v_add_f32_e32 v94, 1.0, v94
	v_add_f32_e32 v90, 1.0, v90
	v_add_f32_e32 v95, 1.0, v95
	v_add_f32_e32 v91, 1.0, v91
	v_rcp_f32_e32 v92, v92
	v_rcp_f32_e32 v88, v88
	v_rcp_f32_e32 v93, v93
	v_rcp_f32_e32 v89, v89
	v_rcp_f32_e32 v94, v94
	v_rcp_f32_e32 v90, v90
	v_rcp_f32_e32 v95, v95
	v_rcp_f32_e32 v91, v91
	v_pk_add_f32 v[86:87], v[86:87], v[110:111]
	v_pk_add_f32 v[84:85], v[84:85], v[108:109]
	v_pk_add_f32 v[82:83], v[82:83], v[106:107]
	v_pk_add_f32 v[80:81], v[80:81], v[104:105]
	v_lshlrev_b32_e32 v134, 16, v120
	v_and_b32_e32 v120, 0xffff0000, v120
	v_lshlrev_b32_e32 v135, 16, v121
	v_and_b32_e32 v121, 0xffff0000, v121
	v_lshlrev_b32_e32 v136, 16, v122
	v_and_b32_e32 v122, 0xffff0000, v122
	v_lshlrev_b32_e32 v137, 16, v123
	v_and_b32_e32 v123, 0xffff0000, v123
	v_mul_f32_e32 v116, v116, v134
	v_mul_f32_e32 v134, v112, v136
	v_mul_f32_e32 v112, v117, v120
	v_mul_f32_e32 v117, v113, v122
	v_mul_f32_e32 v113, v118, v135
	v_mul_f32_e32 v118, v114, v137
	v_mul_f32_e32 v114, v119, v121
	v_mul_f32_e32 v115, v115, v123
	v_cvt_pk_bf16_f32 v112, v116, v112
	v_cvt_pk_bf16_f32 v113, v113, v114
	v_cvt_pk_bf16_f32 v114, v134, v117
	v_cvt_pk_bf16_f32 v115, v118, v115
	global_store_dwordx4 v[128:129], v[112:115], off
	s_nop 1
	v_mov_b32_e32 v112, v198
	v_mov_b32_e32 v113, v199
	v_mov_b32_e32 v114, v200
	v_mov_b32_e32 v115, v201
	v_lshl_add_u64 v[116:117], v[150:151], 0, s[4:5]
	v_lshl_add_u64 v[118:119], v[116:117], 0, v[148:149]
	v_lshl_add_u64 v[120:121], s[26:27], 0, v[126:127]
; __device__ __forceinline__ float sigm(float x) { return __builtin_amdgcn_rcpf(1.f + __builtin_amdgcn_exp2f(-1.4426950409f * x)); }
; __device__ __forceinline__ u32x4 pack8(const f32x4 v0, const f32x4 v1) { u32x4 w; w.x = cvt_pk_bf16(v0[0], v0[1]); w.y = cvt_pk_bf16(v0[2], v0[3]); w.z = cvt_pk_bf16(v1[0], v1[1]); w.w = cvt_pk_bf16(v1[2], v1[3]); return w; }
; __device__ __forceinline__ void unpack8(const u32x4 w, f32x4& lo, f32x4& hi) { lo = (f32x4){bf_lo(w.x), bf_hi(w.x), bf_lo(w.y), bf_hi(w.y)}; hi = (f32x4){bf_lo(w.z), bf_hi(w.z), bf_lo(w.w), bf_hi(w.w)}; }
;     __device__ __forceinline__ void operator()(AccT& acc, const Unit& u, int wr, int wc, int fr, int fq) const {
;     ...
;                     for (int m = 0; m < 4; ++m) { const size_t off = (size_t)(row0 + ai * 128 + m * 16) * DSS + col0 + bj * 128;
;                         f32x4 y0, y1; unpack8(*(const u32x4*)(YG + off), y0, y1);
;                         f32x4 v0 = acc[ai][bj][m][0] + b0, v1 = acc[ai][bj][m][1] + b1;
; #pragma unroll
;                         for (int j = 0; j < 4; ++j) { v0[j] = y0[j] * sigm(v0[j]); v1[j] = y1[j] * sigm(v1[j]); }
;                         *(u32x4*)(YS + off) = pack8(v0, v1); } }
	v_lshlrev_b64 v[118:119], 1, v[118:119]
	v_lshl_add_u64 v[122:123], s[14:15], 0, v[118:119]
	s_mov_b64 s[4:5], 0x48000
	v_mul_f32_e32 v84, 0xbfb8aa3b, v84
	v_mul_f32_e32 v80, 0xbfb8aa3b, v80
	v_mul_f32_e32 v85, 0xbfb8aa3b, v85
	v_mul_f32_e32 v81, 0xbfb8aa3b, v81
	v_mul_f32_e32 v86, 0xbfb8aa3b, v86
	v_mul_f32_e32 v82, 0xbfb8aa3b, v82
	v_mul_f32_e32 v87, 0xbfb8aa3b, v87
	v_mul_f32_e32 v83, 0xbfb8aa3b, v83
	v_exp_f32_e32 v84, v84
	v_exp_f32_e32 v80, v80
	v_exp_f32_e32 v85, v85
	v_exp_f32_e32 v81, v81
	v_exp_f32_e32 v86, v86
	v_exp_f32_e32 v82, v82
	v_exp_f32_e32 v87, v87
	v_exp_f32_e32 v83, v83
	v_add_f32_e32 v84, 1.0, v84
	v_add_f32_e32 v80, 1.0, v80
	v_add_f32_e32 v85, 1.0, v85
	v_add_f32_e32 v81, 1.0, v81
	v_add_f32_e32 v86, 1.0, v86
	v_add_f32_e32 v82, 1.0, v82
	v_add_f32_e32 v87, 1.0, v87
	v_add_f32_e32 v83, 1.0, v83
	v_rcp_f32_e32 v84, v84
	v_rcp_f32_e32 v80, v80
	v_rcp_f32_e32 v85, v85
	v_rcp_f32_e32 v81, v81
	v_rcp_f32_e32 v86, v86
	v_rcp_f32_e32 v82, v82
	v_rcp_f32_e32 v87, v87
	v_rcp_f32_e32 v83, v83
	v_pk_add_f32 v[78:79], v[78:79], v[110:111]
	v_pk_add_f32 v[76:77], v[76:77], v[108:109]
	v_pk_add_f32 v[74:75], v[74:75], v[106:107]
	v_pk_add_f32 v[72:73], v[72:73], v[104:105]
	v_mul_f32_e32 v76, 0xbfb8aa3b, v76
	v_mul_f32_e32 v72, 0xbfb8aa3b, v72
	v_mul_f32_e32 v77, 0xbfb8aa3b, v77
	v_mul_f32_e32 v73, 0xbfb8aa3b, v73
	v_mul_f32_e32 v78, 0xbfb8aa3b, v78
	v_mul_f32_e32 v74, 0xbfb8aa3b, v74
	v_mul_f32_e32 v79, 0xbfb8aa3b, v79
	v_mul_f32_e32 v75, 0xbfb8aa3b, v75
	v_exp_f32_e32 v76, v76
	v_exp_f32_e32 v72, v72
	v_exp_f32_e32 v77, v77
	v_exp_f32_e32 v73, v73
	v_exp_f32_e32 v78, v78
	v_exp_f32_e32 v74, v74
	v_exp_f32_e32 v79, v79
	v_exp_f32_e32 v75, v75
	v_add_f32_e32 v76, 1.0, v76
	v_add_f32_e32 v72, 1.0, v72
	v_add_f32_e32 v77, 1.0, v77
	v_add_f32_e32 v73, 1.0, v73
	v_add_f32_e32 v78, 1.0, v78
	v_add_f32_e32 v74, 1.0, v74
	v_add_f32_e32 v79, 1.0, v79
	v_add_f32_e32 v75, 1.0, v75
	v_rcp_f32_e32 v76, v76
	v_rcp_f32_e32 v72, v72
	v_rcp_f32_e32 v77, v77
	v_rcp_f32_e32 v73, v73
	v_rcp_f32_e32 v78, v78
	v_rcp_f32_e32 v74, v74
	v_rcp_f32_e32 v79, v79
	v_rcp_f32_e32 v75, v75
	v_pk_add_f32 v[70:71], v[70:71], v[110:111]
	v_pk_add_f32 v[68:69], v[68:69], v[108:109]
	v_pk_add_f32 v[66:67], v[66:67], v[106:107]
	v_pk_add_f32 v[64:65], v[64:65], v[104:105]
	v_mul_f32_e32 v68, 0xbfb8aa3b, v68
	v_lshlrev_b32_e32 v126, 16, v112
	v_and_b32_e32 v112, 0xffff0000, v112
	v_lshlrev_b32_e32 v127, 16, v113
	v_and_b32_e32 v113, 0xffff0000, v113
	v_lshlrev_b32_e32 v128, 16, v114
	v_and_b32_e32 v114, 0xffff0000, v114
	v_lshlrev_b32_e32 v129, 16, v115
	v_and_b32_e32 v115, 0xffff0000, v115
	v_mul_f32_e32 v100, v100, v126
	v_mul_f32_e32 v126, v96, v128
	v_mul_f32_e32 v96, v101, v112
	v_mul_f32_e32 v101, v97, v114
	v_mul_f32_e32 v97, v102, v127
	v_mul_f32_e32 v102, v98, v129
	v_mul_f32_e32 v98, v103, v113
	v_mul_f32_e32 v99, v99, v115
	v_cvt_pk_bf16_f32 v96, v100, v96
	v_cvt_pk_bf16_f32 v97, v97, v98
	v_cvt_pk_bf16_f32 v98, v126, v101
	v_cvt_pk_bf16_f32 v99, v102, v99
	global_store_dwordx4 v[120:121], v[96:99], off
	s_nop 1
	v_mov_b32_e32 v96, v202
	v_mov_b32_e32 v97, v203
	v_mov_b32_e32 v98, v204
	v_mov_b32_e32 v99, v205
	v_lshl_add_u64 v[100:101], v[150:151], 0, s[4:5]
	v_lshl_add_u64 v[102:103], v[100:101], 0, v[148:149]
	v_lshl_add_u64 v[112:113], s[26:27], 0, v[118:119]
	v_lshlrev_b64 v[102:103], 1, v[102:103]
	v_lshl_add_u64 v[114:115], s[14:15], 0, v[102:103]
	s_mov_b64 s[4:5], 0x50000
	v_mul_f32_e32 v64, 0xbfb8aa3b, v64
	v_mul_f32_e32 v69, 0xbfb8aa3b, v69
	v_mul_f32_e32 v65, 0xbfb8aa3b, v65
	v_mul_f32_e32 v70, 0xbfb8aa3b, v70
	v_mul_f32_e32 v66, 0xbfb8aa3b, v66
	v_mul_f32_e32 v71, 0xbfb8aa3b, v71
	v_mul_f32_e32 v67, 0xbfb8aa3b, v67
	v_exp_f32_e32 v68, v68
	v_exp_f32_e32 v64, v64
	v_exp_f32_e32 v69, v69
	v_exp_f32_e32 v65, v65
	v_exp_f32_e32 v70, v70
	v_exp_f32_e32 v66, v66
	v_exp_f32_e32 v71, v71
	v_exp_f32_e32 v67, v67
	v_add_f32_e32 v68, 1.0, v68
	v_add_f32_e32 v64, 1.0, v64
	v_add_f32_e32 v69, 1.0, v69
	v_add_f32_e32 v65, 1.0, v65
	v_add_f32_e32 v70, 1.0, v70
	v_add_f32_e32 v66, 1.0, v66
	v_add_f32_e32 v71, 1.0, v71
	v_add_f32_e32 v67, 1.0, v67
	v_rcp_f32_e32 v68, v68
	v_rcp_f32_e32 v64, v64
	v_rcp_f32_e32 v69, v69
	v_rcp_f32_e32 v65, v65
	v_rcp_f32_e32 v70, v70
	v_rcp_f32_e32 v66, v66
	v_rcp_f32_e32 v71, v71
	v_rcp_f32_e32 v67, v67
	v_lshlrev_b32_e32 v118, 16, v96
	v_and_b32_e32 v96, 0xffff0000, v96
	v_lshlrev_b32_e32 v119, 16, v97
	v_and_b32_e32 v97, 0xffff0000, v97
	v_lshlrev_b32_e32 v120, 16, v98
	v_and_b32_e32 v98, 0xffff0000, v98
	v_lshlrev_b32_e32 v121, 16, v99
	v_and_b32_e32 v99, 0xffff0000, v99
	v_mul_f32_e32 v92, v92, v118
	v_mul_f32_e32 v118, v88, v120
	v_mul_f32_e32 v88, v93, v96
	v_mul_f32_e32 v93, v89, v98
	v_mul_f32_e32 v89, v94, v119
	v_mul_f32_e32 v94, v90, v121
	v_mul_f32_e32 v90, v95, v97
	v_mul_f32_e32 v91, v91, v99
	v_cvt_pk_bf16_f32 v88, v92, v88
	v_cvt_pk_bf16_f32 v89, v89, v90
	v_cvt_pk_bf16_f32 v90, v118, v93
	v_cvt_pk_bf16_f32 v91, v94, v91
	global_store_dwordx4 v[112:113], v[88:91], off
	s_nop 1
	v_mov_b32_e32 v88, v206
	v_mov_b32_e32 v89, v207
	v_mov_b32_e32 v90, v208
	v_mov_b32_e32 v91, v209
	v_lshl_add_u64 v[92:93], v[150:151], 0, s[4:5]
	v_lshl_add_u64 v[94:95], v[92:93], 0, v[148:149]
	v_lshl_add_u64 v[96:97], s[26:27], 0, v[102:103]
	v_lshlrev_b64 v[94:95], 1, v[94:95]
	v_lshl_add_u64 v[98:99], s[14:15], 0, v[94:95]
	s_mov_b64 s[4:5], 0x58000
	v_lshlrev_b32_e32 v102, 16, v88
	v_and_b32_e32 v88, 0xffff0000, v88
	v_lshlrev_b32_e32 v103, 16, v89
	v_and_b32_e32 v89, 0xffff0000, v89
	v_lshlrev_b32_e32 v112, 16, v90
	v_and_b32_e32 v90, 0xffff0000, v90
	v_lshlrev_b32_e32 v113, 16, v91
	v_and_b32_e32 v91, 0xffff0000, v91
; __device__ __forceinline__ float sigm(float x) { return __builtin_amdgcn_rcpf(1.f + __builtin_amdgcn_exp2f(-1.4426950409f * x)); }
; __device__ __forceinline__ u32x4 pack8(const f32x4 v0, const f32x4 v1) { u32x4 w; w.x = cvt_pk_bf16(v0[0], v0[1]); w.y = cvt_pk_bf16(v0[2], v0[3]); w.z = cvt_pk_bf16(v1[0], v1[1]); w.w = cvt_pk_bf16(v1[2], v1[3]); return w; }
; __device__ __forceinline__ void unpack8(const u32x4 w, f32x4& lo, f32x4& hi) { lo = (f32x4){bf_lo(w.x), bf_hi(w.x), bf_lo(w.y), bf_hi(w.y)}; hi = (f32x4){bf_lo(w.z), bf_hi(w.z), bf_lo(w.w), bf_hi(w.w)}; }
;     __device__ __forceinline__ void operator()(AccT& acc, const Unit& u, int wr, int wc, int fr, int fq) const {
;     ...
;                     for (int m = 0; m < 4; ++m) { const size_t off = (size_t)(row0 + ai * 128 + m * 16) * DSS + col0 + bj * 128;
;                         f32x4 y0, y1; unpack8(*(const u32x4*)(YG + off), y0, y1);
;                         f32x4 v0 = acc[ai][bj][m][0] + b0, v1 = acc[ai][bj][m][1] + b1;
; #pragma unroll
;                         for (int j = 0; j < 4; ++j) { v0[j] = y0[j] * sigm(v0[j]); v1[j] = y1[j] * sigm(v1[j]); }
;                         *(u32x4*)(YS + off) = pack8(v0, v1); } }
;         } else {
; #pragma unroll
;             for (int bj = 0; bj < 2; ++bj) { const f32x4 b0 = *(const f32x4*)(pool_b + col0 + bj * 128), b1 = *(const f32x4*)(pool_b + col0 + bj * 128 + 4);
	v_mul_f32_e32 v84, v84, v102
	v_mul_f32_e32 v102, v80, v112
	v_mul_f32_e32 v80, v85, v88
	v_mul_f32_e32 v85, v81, v90
	v_mul_f32_e32 v81, v86, v103
	v_mul_f32_e32 v86, v82, v113
	v_mul_f32_e32 v82, v87, v89
	v_mul_f32_e32 v83, v83, v91
	v_cvt_pk_bf16_f32 v80, v84, v80
	v_cvt_pk_bf16_f32 v81, v81, v82
	v_cvt_pk_bf16_f32 v82, v102, v85
	v_cvt_pk_bf16_f32 v83, v86, v83
	global_store_dwordx4 v[96:97], v[80:83], off
	s_nop 1
	v_mov_b32_e32 v80, v210
	v_mov_b32_e32 v81, v211
	v_mov_b32_e32 v82, v212
	v_mov_b32_e32 v83, v213
	v_lshl_add_u64 v[84:85], v[150:151], 0, s[4:5]
	v_lshl_add_u64 v[86:87], v[84:85], 0, v[148:149]
	v_lshl_add_u64 v[88:89], s[26:27], 0, v[94:95]
	v_lshlrev_b64 v[86:87], 1, v[86:87]
	v_lshl_add_u64 v[90:91], s[14:15], 0, v[86:87]
	v_or_b32_e32 v148, 0x80, v148
	v_lshlrev_b32_e32 v94, 16, v80
	v_and_b32_e32 v80, 0xffff0000, v80
	v_lshlrev_b32_e32 v95, 16, v81
	v_and_b32_e32 v81, 0xffff0000, v81
	v_lshlrev_b32_e32 v96, 16, v82
	v_and_b32_e32 v82, 0xffff0000, v82
	v_lshlrev_b32_e32 v97, 16, v83
	v_and_b32_e32 v83, 0xffff0000, v83
	v_mul_f32_e32 v76, v76, v94
	v_mul_f32_e32 v94, v72, v96
	v_mul_f32_e32 v72, v77, v80
	v_mul_f32_e32 v77, v73, v82
	v_mul_f32_e32 v73, v78, v95
	v_mul_f32_e32 v78, v74, v97
	v_mul_f32_e32 v74, v79, v81
	v_mul_f32_e32 v75, v75, v83
	v_cvt_pk_bf16_f32 v72, v76, v72
	v_cvt_pk_bf16_f32 v73, v73, v74
	v_cvt_pk_bf16_f32 v74, v94, v77
	v_cvt_pk_bf16_f32 v75, v78, v75
	global_store_dwordx4 v[88:89], v[72:75], off
	s_nop 1
	v_mov_b32_e32 v72, v214
	v_mov_b32_e32 v73, v215
	v_mov_b32_e32 v74, v216
	v_mov_b32_e32 v75, v217
	v_lshl_add_u64 v[76:77], v[148:149], 0, v[150:151]
	v_lshl_add_u64 v[78:79], s[26:27], 0, v[86:87]
	v_lshlrev_b64 v[76:77], 1, v[76:77]
	v_lshl_add_u64 v[80:81], s[14:15], 0, v[76:77]
	v_lshl_add_u64 v[76:77], s[26:27], 0, v[76:77]
	v_lshlrev_b32_e32 v82, 16, v72
	v_and_b32_e32 v72, 0xffff0000, v72
	v_lshlrev_b32_e32 v83, 16, v73
	v_and_b32_e32 v73, 0xffff0000, v73
	v_lshlrev_b32_e32 v86, 16, v74
	v_and_b32_e32 v74, 0xffff0000, v74
	v_lshlrev_b32_e32 v87, 16, v75
	v_and_b32_e32 v75, 0xffff0000, v75
	v_mul_f32_e32 v68, v68, v82
	v_mul_f32_e32 v82, v64, v86
	v_mul_f32_e32 v64, v69, v72
	v_mul_f32_e32 v69, v65, v74
	v_mul_f32_e32 v65, v70, v83
	v_mul_f32_e32 v70, v66, v87
	v_mul_f32_e32 v66, v71, v73
	v_mul_f32_e32 v67, v67, v75
	v_cvt_pk_bf16_f32 v64, v68, v64
	v_cvt_pk_bf16_f32 v65, v65, v66
	v_cvt_pk_bf16_f32 v66, v82, v69
	v_cvt_pk_bf16_f32 v67, v70, v67
	global_store_dwordx4 v[78:79], v[64:67], off
	v_mov_b32_e32 v72, v218
	v_mov_b32_e32 v73, v219
	v_mov_b32_e32 v74, v220
	v_mov_b32_e32 v75, v221
	global_load_dwordx4 v[68:71], v[140:141], off offset:512
	s_nop 0
	global_load_dwordx4 v[64:67], v[140:141], off offset:528
	v_lshl_add_u64 v[78:79], v[148:149], 0, v[142:143]
	v_lshlrev_b64 v[78:79], 1, v[78:79]
	v_lshl_add_u64 v[80:81], s[14:15], 0, v[78:79]
	s_waitcnt vmcnt(2)
	v_lshlrev_b32_e32 v82, 16, v72
	s_waitcnt vmcnt(1)
	v_pk_add_f32 v[62:63], v[62:63], v[70:71]
	v_pk_add_f32 v[60:61], v[60:61], v[68:69]
	s_waitcnt vmcnt(0)
	v_pk_add_f32 v[58:59], v[58:59], v[66:67]
	v_pk_add_f32 v[56:57], v[56:57], v[64:65]
	v_mul_f32_e32 v60, 0xbfb8aa3b, v60
	v_mul_f32_e32 v56, 0xbfb8aa3b, v56
	v_mul_f32_e32 v61, 0xbfb8aa3b, v61
	v_mul_f32_e32 v57, 0xbfb8aa3b, v57
	v_mul_f32_e32 v62, 0xbfb8aa3b, v62
	v_mul_f32_e32 v58, 0xbfb8aa3b, v58
	v_mul_f32_e32 v63, 0xbfb8aa3b, v63
	v_mul_f32_e32 v59, 0xbfb8aa3b, v59
	v_exp_f32_e32 v60, v60
	v_exp_f32_e32 v56, v56
	v_exp_f32_e32 v61, v61
	v_exp_f32_e32 v57, v57
	v_exp_f32_e32 v62, v62
	v_exp_f32_e32 v58, v58
	v_exp_f32_e32 v63, v63
	v_exp_f32_e32 v59, v59
	v_add_f32_e32 v60, 1.0, v60
	v_add_f32_e32 v56, 1.0, v56
	v_add_f32_e32 v61, 1.0, v61
	v_add_f32_e32 v57, 1.0, v57
	v_add_f32_e32 v62, 1.0, v62
	v_add_f32_e32 v58, 1.0, v58
	v_add_f32_e32 v63, 1.0, v63
	v_add_f32_e32 v59, 1.0, v59
	v_rcp_f32_e32 v60, v60
	v_rcp_f32_e32 v56, v56
	v_rcp_f32_e32 v61, v61
	v_rcp_f32_e32 v57, v57
	v_rcp_f32_e32 v62, v62
	v_rcp_f32_e32 v58, v58
	v_rcp_f32_e32 v63, v63
	v_rcp_f32_e32 v59, v59
	v_and_b32_e32 v72, 0xffff0000, v72
	v_lshlrev_b32_e32 v83, 16, v73
	v_and_b32_e32 v73, 0xffff0000, v73
	v_lshlrev_b32_e32 v86, 16, v74
	v_and_b32_e32 v74, 0xffff0000, v74
	v_lshlrev_b32_e32 v87, 16, v75
	v_and_b32_e32 v75, 0xffff0000, v75
	v_mul_f32_e32 v60, v60, v82
	v_mul_f32_e32 v82, v56, v86
	v_mul_f32_e32 v56, v61, v72
	v_mul_f32_e32 v61, v57, v74
	v_mul_f32_e32 v57, v62, v83
	v_mul_f32_e32 v62, v58, v87
	v_mul_f32_e32 v58, v63, v73
	v_mul_f32_e32 v59, v59, v75
	v_cvt_pk_bf16_f32 v56, v60, v56
	v_cvt_pk_bf16_f32 v57, v57, v58
	v_cvt_pk_bf16_f32 v58, v82, v61
	v_cvt_pk_bf16_f32 v59, v62, v59
	global_store_dwordx4 v[76:77], v[56:59], off
	s_nop 1
	v_mov_b32_e32 v56, v222
	v_mov_b32_e32 v57, v223
	v_mov_b32_e32 v58, v224
	v_mov_b32_e32 v59, v225
	v_pk_add_f32 v[54:55], v[54:55], v[70:71]
	v_pk_add_f32 v[52:53], v[52:53], v[68:69]
	v_pk_add_f32 v[50:51], v[50:51], v[66:67]
	v_pk_add_f32 v[48:49], v[48:49], v[64:65]
	v_mul_f32_e32 v52, 0xbfb8aa3b, v52
	v_mul_f32_e32 v48, 0xbfb8aa3b, v48
	v_mul_f32_e32 v53, 0xbfb8aa3b, v53
	v_mul_f32_e32 v49, 0xbfb8aa3b, v49
	v_mul_f32_e32 v54, 0xbfb8aa3b, v54
	v_mul_f32_e32 v50, 0xbfb8aa3b, v50
	v_mul_f32_e32 v55, 0xbfb8aa3b, v55
	v_mul_f32_e32 v51, 0xbfb8aa3b, v51
	v_exp_f32_e32 v52, v52
	v_exp_f32_e32 v48, v48
	v_exp_f32_e32 v53, v53
	v_exp_f32_e32 v49, v49
	v_exp_f32_e32 v54, v54
	v_exp_f32_e32 v50, v50
	v_exp_f32_e32 v55, v55
	v_exp_f32_e32 v51, v51
	v_add_f32_e32 v52, 1.0, v52
	v_add_f32_e32 v48, 1.0, v48
	v_add_f32_e32 v53, 1.0, v53
	v_add_f32_e32 v49, 1.0, v49
	v_add_f32_e32 v54, 1.0, v54
	v_add_f32_e32 v50, 1.0, v50
	v_add_f32_e32 v55, 1.0, v55
; __device__ __forceinline__ float sigm(float x) { return __builtin_amdgcn_rcpf(1.f + __builtin_amdgcn_exp2f(-1.4426950409f * x)); }
; __device__ __forceinline__ u32x4 pack8(const f32x4 v0, const f32x4 v1) { u32x4 w; w.x = cvt_pk_bf16(v0[0], v0[1]); w.y = cvt_pk_bf16(v0[2], v0[3]); w.z = cvt_pk_bf16(v1[0], v1[1]); w.w = cvt_pk_bf16(v1[2], v1[3]); return w; }
; __device__ __forceinline__ void unpack8(const u32x4 w, f32x4& lo, f32x4& hi) { lo = (f32x4){bf_lo(w.x), bf_hi(w.x), bf_lo(w.y), bf_hi(w.y)}; hi = (f32x4){bf_lo(w.z), bf_hi(w.z), bf_lo(w.w), bf_hi(w.w)}; }
;     __device__ __forceinline__ void operator()(AccT& acc, const Unit& u, int wr, int wc, int fr, int fq) const {
;     ...
;                     for (int m = 0; m < 4; ++m) { const size_t off = (size_t)(row0 + ai * 128 + m * 16) * DSS + col0 + bj * 128;
;                         f32x4 y0, y1; unpack8(*(const u32x4*)(YG + off), y0, y1);
;                         f32x4 v0 = acc[ai][bj][m][0] + b0, v1 = acc[ai][bj][m][1] + b1;
; #pragma unroll
;                         for (int j = 0; j < 4; ++j) { v0[j] = y0[j] * sigm(v0[j]); v1[j] = y1[j] * sigm(v1[j]); }
;                         *(u32x4*)(YS + off) = pack8(v0, v1); } }
	v_add_f32_e32 v51, 1.0, v51
	v_rcp_f32_e32 v52, v52
	v_rcp_f32_e32 v48, v48
	v_rcp_f32_e32 v53, v53
	v_rcp_f32_e32 v49, v49
	v_rcp_f32_e32 v54, v54
	v_rcp_f32_e32 v50, v50
	v_rcp_f32_e32 v55, v55
	v_rcp_f32_e32 v51, v51
	v_lshl_add_u64 v[60:61], v[148:149], 0, v[132:133]
	v_lshlrev_b64 v[60:61], 1, v[60:61]
	v_lshl_add_u64 v[62:63], s[26:27], 0, v[78:79]
	v_lshl_add_u64 v[72:73], s[14:15], 0, v[60:61]
	v_pk_add_f32 v[46:47], v[46:47], v[70:71]
	v_pk_add_f32 v[44:45], v[44:45], v[68:69]
	v_pk_add_f32 v[42:43], v[42:43], v[66:67]
	v_pk_add_f32 v[40:41], v[40:41], v[64:65]
	v_mul_f32_e32 v44, 0xbfb8aa3b, v44
	v_mul_f32_e32 v40, 0xbfb8aa3b, v40
	v_mul_f32_e32 v45, 0xbfb8aa3b, v45
	v_mul_f32_e32 v41, 0xbfb8aa3b, v41
	v_mul_f32_e32 v46, 0xbfb8aa3b, v46
	v_mul_f32_e32 v42, 0xbfb8aa3b, v42
	v_mul_f32_e32 v47, 0xbfb8aa3b, v47
	v_mul_f32_e32 v43, 0xbfb8aa3b, v43
	v_exp_f32_e32 v44, v44
	v_exp_f32_e32 v40, v40
	v_exp_f32_e32 v45, v45
	v_exp_f32_e32 v41, v41
	v_exp_f32_e32 v46, v46
	v_exp_f32_e32 v42, v42
	v_exp_f32_e32 v47, v47
	v_exp_f32_e32 v43, v43
	v_add_f32_e32 v44, 1.0, v44
	v_add_f32_e32 v40, 1.0, v40
	v_add_f32_e32 v45, 1.0, v45
	v_add_f32_e32 v41, 1.0, v41
	v_add_f32_e32 v46, 1.0, v46
	v_add_f32_e32 v42, 1.0, v42
	v_add_f32_e32 v47, 1.0, v47
	v_add_f32_e32 v43, 1.0, v43
	v_rcp_f32_e32 v44, v44
	v_rcp_f32_e32 v40, v40
	v_rcp_f32_e32 v45, v45
	v_rcp_f32_e32 v41, v41
	v_rcp_f32_e32 v46, v46
	v_rcp_f32_e32 v42, v42
	v_rcp_f32_e32 v47, v47
	v_rcp_f32_e32 v43, v43
	v_pk_add_f32 v[38:39], v[38:39], v[70:71]
	v_pk_add_f32 v[36:37], v[36:37], v[68:69]
	v_pk_add_f32 v[34:35], v[34:35], v[66:67]
	v_lshlrev_b32_e32 v74, 16, v56
	v_and_b32_e32 v56, 0xffff0000, v56
	v_lshlrev_b32_e32 v75, 16, v57
	v_and_b32_e32 v57, 0xffff0000, v57
	v_lshlrev_b32_e32 v76, 16, v58
	v_and_b32_e32 v58, 0xffff0000, v58
	v_lshlrev_b32_e32 v77, 16, v59
	v_and_b32_e32 v59, 0xffff0000, v59
	v_mul_f32_e32 v52, v52, v74
	v_mul_f32_e32 v74, v48, v76
	v_mul_f32_e32 v48, v53, v56
	v_mul_f32_e32 v53, v49, v58
	v_mul_f32_e32 v49, v54, v75
	v_mul_f32_e32 v54, v50, v77
	v_mul_f32_e32 v50, v55, v57
	v_mul_f32_e32 v51, v51, v59
	v_cvt_pk_bf16_f32 v48, v52, v48
	v_cvt_pk_bf16_f32 v49, v49, v50
	v_cvt_pk_bf16_f32 v50, v74, v53
	v_cvt_pk_bf16_f32 v51, v54, v51
	global_store_dwordx4 v[62:63], v[48:51], off
	s_nop 1
	v_mov_b32_e32 v48, v226
	v_mov_b32_e32 v49, v227
	v_mov_b32_e32 v50, v228
	v_mov_b32_e32 v51, v229
	v_lshl_add_u64 v[52:53], v[148:149], 0, v[124:125]
	v_lshl_add_u64 v[54:55], s[26:27], 0, v[60:61]
	v_lshlrev_b64 v[52:53], 1, v[52:53]
	v_lshl_add_u64 v[56:57], s[14:15], 0, v[52:53]
	v_pk_add_f32 v[32:33], v[32:33], v[64:65]
	v_mul_f32_e32 v36, 0xbfb8aa3b, v36
	v_mul_f32_e32 v32, 0xbfb8aa3b, v32
	v_mul_f32_e32 v37, 0xbfb8aa3b, v37
	v_mul_f32_e32 v33, 0xbfb8aa3b, v33
	v_mul_f32_e32 v38, 0xbfb8aa3b, v38
	v_mul_f32_e32 v34, 0xbfb8aa3b, v34
	v_mul_f32_e32 v39, 0xbfb8aa3b, v39
	v_mul_f32_e32 v35, 0xbfb8aa3b, v35
	v_exp_f32_e32 v36, v36
	v_exp_f32_e32 v32, v32
	v_exp_f32_e32 v37, v37
	v_exp_f32_e32 v33, v33
	v_exp_f32_e32 v38, v38
	v_exp_f32_e32 v34, v34
	v_exp_f32_e32 v39, v39
	v_exp_f32_e32 v35, v35
	v_add_f32_e32 v36, 1.0, v36
	v_add_f32_e32 v32, 1.0, v32
	v_add_f32_e32 v37, 1.0, v37
	v_add_f32_e32 v33, 1.0, v33
	v_add_f32_e32 v38, 1.0, v38
	v_add_f32_e32 v34, 1.0, v34
	v_add_f32_e32 v39, 1.0, v39
	v_add_f32_e32 v35, 1.0, v35
	v_rcp_f32_e32 v36, v36
	v_rcp_f32_e32 v32, v32
	v_rcp_f32_e32 v37, v37
	v_rcp_f32_e32 v33, v33
	v_rcp_f32_e32 v38, v38
	v_rcp_f32_e32 v34, v34
	v_rcp_f32_e32 v39, v39
	v_rcp_f32_e32 v35, v35
	v_pk_add_f32 v[30:31], v[30:31], v[70:71]
	v_pk_add_f32 v[28:29], v[28:29], v[68:69]
	v_pk_add_f32 v[26:27], v[26:27], v[66:67]
	v_pk_add_f32 v[24:25], v[24:25], v[64:65]
	v_mul_f32_e32 v28, 0xbfb8aa3b, v28
	v_mul_f32_e32 v24, 0xbfb8aa3b, v24
	v_mul_f32_e32 v29, 0xbfb8aa3b, v29
	v_mul_f32_e32 v25, 0xbfb8aa3b, v25
	v_mul_f32_e32 v30, 0xbfb8aa3b, v30
	v_mul_f32_e32 v26, 0xbfb8aa3b, v26
	v_mul_f32_e32 v31, 0xbfb8aa3b, v31
	v_mul_f32_e32 v27, 0xbfb8aa3b, v27
	v_exp_f32_e32 v28, v28
	v_exp_f32_e32 v24, v24
	v_exp_f32_e32 v29, v29
	v_exp_f32_e32 v25, v25
	v_exp_f32_e32 v30, v30
	v_exp_f32_e32 v26, v26
	v_exp_f32_e32 v31, v31
	v_exp_f32_e32 v27, v27
	v_add_f32_e32 v28, 1.0, v28
	v_add_f32_e32 v24, 1.0, v24
	v_add_f32_e32 v29, 1.0, v29
	v_add_f32_e32 v25, 1.0, v25
	v_add_f32_e32 v30, 1.0, v30
	v_add_f32_e32 v26, 1.0, v26
	v_add_f32_e32 v31, 1.0, v31
	v_add_f32_e32 v27, 1.0, v27
	v_rcp_f32_e32 v28, v28
	v_rcp_f32_e32 v24, v24
	v_rcp_f32_e32 v29, v29
	v_rcp_f32_e32 v25, v25
	v_rcp_f32_e32 v30, v30
	v_rcp_f32_e32 v26, v26
	v_rcp_f32_e32 v31, v31
	v_rcp_f32_e32 v27, v27
	v_pk_add_f32 v[22:23], v[22:23], v[70:71]
	v_pk_add_f32 v[20:21], v[20:21], v[68:69]
	v_pk_add_f32 v[18:19], v[18:19], v[66:67]
	v_pk_add_f32 v[16:17], v[16:17], v[64:65]
	v_mul_f32_e32 v20, 0xbfb8aa3b, v20
	v_mul_f32_e32 v16, 0xbfb8aa3b, v16
	v_lshlrev_b32_e32 v58, 16, v48
	v_and_b32_e32 v48, 0xffff0000, v48
	v_lshlrev_b32_e32 v59, 16, v49
	v_and_b32_e32 v49, 0xffff0000, v49
	v_lshlrev_b32_e32 v60, 16, v50
	v_and_b32_e32 v50, 0xffff0000, v50
	v_lshlrev_b32_e32 v61, 16, v51
	v_and_b32_e32 v51, 0xffff0000, v51
	v_mul_f32_e32 v44, v44, v58
	v_mul_f32_e32 v58, v40, v60
	v_mul_f32_e32 v40, v45, v48
	v_mul_f32_e32 v45, v41, v50
	v_mul_f32_e32 v41, v46, v59
	v_mul_f32_e32 v46, v42, v61
	v_mul_f32_e32 v42, v47, v49
	v_mul_f32_e32 v43, v43, v51
	v_cvt_pk_bf16_f32 v40, v44, v40
	v_cvt_pk_bf16_f32 v41, v41, v42
	v_cvt_pk_bf16_f32 v42, v58, v45
	v_cvt_pk_bf16_f32 v43, v46, v43
	global_store_dwordx4 v[54:55], v[40:43], off
	s_nop 1
	v_mov_b32_e32 v40, v230
	v_mov_b32_e32 v41, v231
	v_mov_b32_e32 v42, v232
	v_mov_b32_e32 v43, v233
; __device__ __forceinline__ float sigm(float x) { return __builtin_amdgcn_rcpf(1.f + __builtin_amdgcn_exp2f(-1.4426950409f * x)); }
; __device__ __forceinline__ u32x4 pack8(const f32x4 v0, const f32x4 v1) { u32x4 w; w.x = cvt_pk_bf16(v0[0], v0[1]); w.y = cvt_pk_bf16(v0[2], v0[3]); w.z = cvt_pk_bf16(v1[0], v1[1]); w.w = cvt_pk_bf16(v1[2], v1[3]); return w; }
; __device__ __forceinline__ void unpack8(const u32x4 w, f32x4& lo, f32x4& hi) { lo = (f32x4){bf_lo(w.x), bf_hi(w.x), bf_lo(w.y), bf_hi(w.y)}; hi = (f32x4){bf_lo(w.z), bf_hi(w.z), bf_lo(w.w), bf_hi(w.w)}; }
;     __device__ __forceinline__ void operator()(AccT& acc, const Unit& u, int wr, int wc, int fr, int fq) const {
;     ...
;                     for (int m = 0; m < 4; ++m) { const size_t off = (size_t)(row0 + ai * 128 + m * 16) * DSS + col0 + bj * 128;
;                         f32x4 y0, y1; unpack8(*(const u32x4*)(YG + off), y0, y1);
;                         f32x4 v0 = acc[ai][bj][m][0] + b0, v1 = acc[ai][bj][m][1] + b1;
; #pragma unroll
;                         for (int j = 0; j < 4; ++j) { v0[j] = y0[j] * sigm(v0[j]); v1[j] = y1[j] * sigm(v1[j]); }
;                         *(u32x4*)(YS + off) = pack8(v0, v1); } }
	v_lshl_add_u64 v[44:45], v[148:149], 0, v[116:117]
	v_lshl_add_u64 v[46:47], s[26:27], 0, v[52:53]
	v_lshlrev_b64 v[44:45], 1, v[44:45]
	v_lshl_add_u64 v[48:49], s[14:15], 0, v[44:45]
	v_mul_f32_e32 v21, 0xbfb8aa3b, v21
	v_mul_f32_e32 v17, 0xbfb8aa3b, v17
	v_mul_f32_e32 v22, 0xbfb8aa3b, v22
	v_mul_f32_e32 v18, 0xbfb8aa3b, v18
	v_mul_f32_e32 v23, 0xbfb8aa3b, v23
	v_mul_f32_e32 v19, 0xbfb8aa3b, v19
	v_exp_f32_e32 v20, v20
	v_exp_f32_e32 v16, v16
	v_exp_f32_e32 v21, v21
	v_exp_f32_e32 v17, v17
	v_exp_f32_e32 v22, v22
	v_exp_f32_e32 v18, v18
	v_exp_f32_e32 v23, v23
	v_exp_f32_e32 v19, v19
	v_add_f32_e32 v20, 1.0, v20
	v_add_f32_e32 v16, 1.0, v16
	v_add_f32_e32 v21, 1.0, v21
	v_add_f32_e32 v17, 1.0, v17
	v_add_f32_e32 v22, 1.0, v22
	v_add_f32_e32 v18, 1.0, v18
	v_add_f32_e32 v23, 1.0, v23
	v_add_f32_e32 v19, 1.0, v19
	v_rcp_f32_e32 v20, v20
	v_rcp_f32_e32 v16, v16
	v_rcp_f32_e32 v21, v21
	v_rcp_f32_e32 v17, v17
	v_rcp_f32_e32 v22, v22
	v_rcp_f32_e32 v18, v18
	v_rcp_f32_e32 v23, v23
	v_rcp_f32_e32 v19, v19
	v_pk_add_f32 v[14:15], v[14:15], v[70:71]
	v_pk_add_f32 v[12:13], v[12:13], v[68:69]
	v_pk_add_f32 v[10:11], v[10:11], v[66:67]
	v_pk_add_f32 v[8:9], v[8:9], v[64:65]
	v_mul_f32_e32 v12, 0xbfb8aa3b, v12
	v_mul_f32_e32 v8, 0xbfb8aa3b, v8
	v_mul_f32_e32 v13, 0xbfb8aa3b, v13
	v_mul_f32_e32 v9, 0xbfb8aa3b, v9
	v_mul_f32_e32 v14, 0xbfb8aa3b, v14
	v_mul_f32_e32 v10, 0xbfb8aa3b, v10
	v_mul_f32_e32 v15, 0xbfb8aa3b, v15
	v_mul_f32_e32 v11, 0xbfb8aa3b, v11
	v_exp_f32_e32 v12, v12
	v_exp_f32_e32 v8, v8
	v_exp_f32_e32 v13, v13
	v_exp_f32_e32 v9, v9
	v_exp_f32_e32 v14, v14
	v_exp_f32_e32 v10, v10
	v_exp_f32_e32 v15, v15
	v_exp_f32_e32 v11, v11
	v_add_f32_e32 v12, 1.0, v12
	v_add_f32_e32 v8, 1.0, v8
	v_add_f32_e32 v13, 1.0, v13
	v_add_f32_e32 v9, 1.0, v9
	v_add_f32_e32 v14, 1.0, v14
	v_add_f32_e32 v10, 1.0, v10
	v_add_f32_e32 v15, 1.0, v15
	v_add_f32_e32 v11, 1.0, v11
	v_rcp_f32_e32 v12, v12
	v_rcp_f32_e32 v8, v8
	v_rcp_f32_e32 v13, v13
	v_rcp_f32_e32 v9, v9
	v_rcp_f32_e32 v14, v14
	v_rcp_f32_e32 v10, v10
	v_rcp_f32_e32 v15, v15
	v_rcp_f32_e32 v11, v11
	v_pk_add_f32 v[6:7], v[6:7], v[70:71]
	v_pk_add_f32 v[4:5], v[4:5], v[68:69]
	v_pk_add_f32 v[2:3], v[2:3], v[66:67]
	v_pk_add_f32 v[0:1], v[0:1], v[64:65]
	v_mul_f32_e32 v4, 0xbfb8aa3b, v4
	v_mul_f32_e32 v0, 0xbfb8aa3b, v0
	v_mul_f32_e32 v5, 0xbfb8aa3b, v5
	v_mul_f32_e32 v1, 0xbfb8aa3b, v1
	v_mul_f32_e32 v6, 0xbfb8aa3b, v6
	v_lshlrev_b32_e32 v50, 16, v40
	v_and_b32_e32 v40, 0xffff0000, v40
	v_lshlrev_b32_e32 v51, 16, v41
	v_and_b32_e32 v41, 0xffff0000, v41
	v_lshlrev_b32_e32 v52, 16, v42
	v_and_b32_e32 v42, 0xffff0000, v42
	v_lshlrev_b32_e32 v53, 16, v43
	v_and_b32_e32 v43, 0xffff0000, v43
	v_mul_f32_e32 v36, v36, v50
	v_mul_f32_e32 v50, v32, v52
	v_mul_f32_e32 v32, v37, v40
	v_mul_f32_e32 v37, v33, v42
	v_mul_f32_e32 v33, v38, v51
	v_mul_f32_e32 v38, v34, v53
	v_mul_f32_e32 v34, v39, v41
	v_mul_f32_e32 v35, v35, v43
	v_cvt_pk_bf16_f32 v32, v36, v32
	v_cvt_pk_bf16_f32 v33, v33, v34
	v_cvt_pk_bf16_f32 v34, v50, v37
	v_cvt_pk_bf16_f32 v35, v38, v35
	global_store_dwordx4 v[46:47], v[32:35], off
	s_nop 1
	v_mov_b32_e32 v32, v234
	v_mov_b32_e32 v33, v235
	v_mov_b32_e32 v34, v236
	v_mov_b32_e32 v35, v237
	v_lshl_add_u64 v[36:37], v[148:149], 0, v[100:101]
	v_lshl_add_u64 v[38:39], s[26:27], 0, v[44:45]
	v_lshlrev_b64 v[36:37], 1, v[36:37]
	v_lshl_add_u64 v[40:41], s[14:15], 0, v[36:37]
	v_mul_f32_e32 v2, 0xbfb8aa3b, v2
	v_mul_f32_e32 v7, 0xbfb8aa3b, v7
	v_mul_f32_e32 v3, 0xbfb8aa3b, v3
	v_exp_f32_e32 v4, v4
	v_exp_f32_e32 v0, v0
	v_exp_f32_e32 v5, v5
	v_exp_f32_e32 v1, v1
	v_exp_f32_e32 v6, v6
	v_exp_f32_e32 v2, v2
	v_exp_f32_e32 v7, v7
	v_exp_f32_e32 v3, v3
	v_add_f32_e32 v4, 1.0, v4
	v_add_f32_e32 v0, 1.0, v0
	v_add_f32_e32 v5, 1.0, v5
; __device__ __forceinline__ float sigm(float x) { return __builtin_amdgcn_rcpf(1.f + __builtin_amdgcn_exp2f(-1.4426950409f * x)); }
; __device__ __forceinline__ u32x4 pack8(const f32x4 v0, const f32x4 v1) { u32x4 w; w.x = cvt_pk_bf16(v0[0], v0[1]); w.y = cvt_pk_bf16(v0[2], v0[3]); w.z = cvt_pk_bf16(v1[0], v1[1]); w.w = cvt_pk_bf16(v1[2], v1[3]); return w; }
; __device__ __forceinline__ void unpack8(const u32x4 w, f32x4& lo, f32x4& hi) { lo = (f32x4){bf_lo(w.x), bf_hi(w.x), bf_lo(w.y), bf_hi(w.y)}; hi = (f32x4){bf_lo(w.z), bf_hi(w.z), bf_lo(w.w), bf_hi(w.w)}; }
;     __device__ __forceinline__ void operator()(AccT& acc, const Unit& u, int wr, int wc, int fr, int fq) const {
;     ...
;                     for (int m = 0; m < 4; ++m) { const size_t off = (size_t)(row0 + ai * 128 + m * 16) * DSS + col0 + bj * 128;
;                         f32x4 y0, y1; unpack8(*(const u32x4*)(YG + off), y0, y1);
;                         f32x4 v0 = acc[ai][bj][m][0] + b0, v1 = acc[ai][bj][m][1] + b1;
; #pragma unroll
;                         for (int j = 0; j < 4; ++j) { v0[j] = y0[j] * sigm(v0[j]); v1[j] = y1[j] * sigm(v1[j]); }
;                         *(u32x4*)(YS + off) = pack8(v0, v1); } }
	v_add_f32_e32 v1, 1.0, v1
	v_add_f32_e32 v6, 1.0, v6
	v_add_f32_e32 v2, 1.0, v2
	v_add_f32_e32 v7, 1.0, v7
	v_add_f32_e32 v3, 1.0, v3
	v_rcp_f32_e32 v4, v4
	v_rcp_f32_e32 v0, v0
	v_rcp_f32_e32 v5, v5
	v_rcp_f32_e32 v1, v1
	v_rcp_f32_e32 v6, v6
	v_rcp_f32_e32 v2, v2
	v_rcp_f32_e32 v7, v7
	v_rcp_f32_e32 v3, v3
	v_lshlrev_b32_e32 v42, 16, v32
	v_and_b32_e32 v32, 0xffff0000, v32
	v_lshlrev_b32_e32 v43, 16, v33
	v_and_b32_e32 v33, 0xffff0000, v33
	v_lshlrev_b32_e32 v44, 16, v34
	v_and_b32_e32 v34, 0xffff0000, v34
	v_lshlrev_b32_e32 v45, 16, v35
	v_and_b32_e32 v35, 0xffff0000, v35
	v_mul_f32_e32 v28, v28, v42
	v_mul_f32_e32 v42, v24, v44
	v_mul_f32_e32 v24, v29, v32
	v_mul_f32_e32 v29, v25, v34
	v_mul_f32_e32 v25, v30, v43
	v_mul_f32_e32 v30, v26, v45
	v_mul_f32_e32 v26, v31, v33
	v_mul_f32_e32 v27, v27, v35
	v_cvt_pk_bf16_f32 v24, v28, v24
	v_cvt_pk_bf16_f32 v25, v25, v26
	v_cvt_pk_bf16_f32 v26, v42, v29
	v_cvt_pk_bf16_f32 v27, v30, v27
	global_store_dwordx4 v[38:39], v[24:27], off
	s_nop 1
	v_mov_b32_e32 v24, v238
	v_mov_b32_e32 v25, v239
	v_mov_b32_e32 v26, v240
	v_mov_b32_e32 v27, v241
	v_lshl_add_u64 v[28:29], v[148:149], 0, v[92:93]
	v_lshl_add_u64 v[30:31], s[26:27], 0, v[36:37]
	v_lshlrev_b64 v[28:29], 1, v[28:29]
	v_lshl_add_u64 v[32:33], s[14:15], 0, v[28:29]
	v_lshlrev_b32_e32 v34, 16, v24
	v_and_b32_e32 v24, 0xffff0000, v24
	v_lshlrev_b32_e32 v35, 16, v25
	v_and_b32_e32 v25, 0xffff0000, v25
	v_lshlrev_b32_e32 v36, 16, v26
	v_and_b32_e32 v26, 0xffff0000, v26
	v_lshlrev_b32_e32 v37, 16, v27
	v_and_b32_e32 v27, 0xffff0000, v27
	v_mul_f32_e32 v20, v20, v34
	v_mul_f32_e32 v34, v16, v36
	v_mul_f32_e32 v16, v21, v24
	v_mul_f32_e32 v21, v17, v26
	v_mul_f32_e32 v17, v22, v35
	v_mul_f32_e32 v22, v18, v37
	v_mul_f32_e32 v18, v23, v25
	v_mul_f32_e32 v19, v19, v27
	v_cvt_pk_bf16_f32 v16, v20, v16
	v_cvt_pk_bf16_f32 v17, v17, v18
	v_cvt_pk_bf16_f32 v18, v34, v21
	v_cvt_pk_bf16_f32 v19, v22, v19
	global_store_dwordx4 v[30:31], v[16:19], off
	s_nop 1
	v_mov_b32_e32 v16, v242
	v_mov_b32_e32 v17, v243
	v_mov_b32_e32 v18, v244
	v_mov_b32_e32 v19, v245
	v_lshl_add_u64 v[20:21], v[148:149], 0, v[84:85]
	v_lshl_add_u64 v[22:23], s[26:27], 0, v[28:29]
	v_lshlrev_b64 v[20:21], 1, v[20:21]
	v_lshl_add_u64 v[24:25], s[14:15], 0, v[20:21]
	v_lshlrev_b32_e32 v26, 16, v16
	v_and_b32_e32 v16, 0xffff0000, v16
	v_lshlrev_b32_e32 v27, 16, v17
	v_and_b32_e32 v17, 0xffff0000, v17
	v_lshlrev_b32_e32 v28, 16, v18
	v_and_b32_e32 v18, 0xffff0000, v18
	v_lshlrev_b32_e32 v29, 16, v19
	v_and_b32_e32 v19, 0xffff0000, v19
	v_mul_f32_e32 v12, v12, v26
	v_mul_f32_e32 v26, v8, v28
	v_mul_f32_e32 v8, v13, v16
	v_mul_f32_e32 v13, v9, v18
	v_mul_f32_e32 v9, v14, v27
	v_mul_f32_e32 v14, v10, v29
	v_mul_f32_e32 v10, v15, v17
	v_mul_f32_e32 v11, v11, v19
	v_cvt_pk_bf16_f32 v8, v12, v8
	v_cvt_pk_bf16_f32 v9, v9, v10
	v_cvt_pk_bf16_f32 v10, v26, v13
	v_cvt_pk_bf16_f32 v11, v14, v11
	global_store_dwordx4 v[22:23], v[8:11], off
	s_nop 1
	v_mov_b32_e32 v8, v246
	v_mov_b32_e32 v9, v247
	v_mov_b32_e32 v10, v248
	v_mov_b32_e32 v11, v249
	v_lshlrev_b32_e32 v12, 16, v8
	v_and_b32_e32 v8, 0xffff0000, v8
	v_lshlrev_b32_e32 v13, 16, v9
	v_and_b32_e32 v9, 0xffff0000, v9
	v_lshlrev_b32_e32 v14, 16, v10
	v_and_b32_e32 v10, 0xffff0000, v10
	v_lshlrev_b32_e32 v15, 16, v11
	v_and_b32_e32 v11, 0xffff0000, v11
	v_mul_f32_e32 v4, v4, v12
	v_mul_f32_e32 v12, v0, v14
	v_mul_f32_e32 v0, v5, v8
	v_mul_f32_e32 v5, v1, v10
	v_mul_f32_e32 v1, v6, v13
	v_mul_f32_e32 v6, v2, v15
	v_mul_f32_e32 v2, v7, v9
	v_mul_f32_e32 v3, v3, v11
	v_cvt_pk_bf16_f32 v0, v4, v0
	v_cvt_pk_bf16_f32 v1, v1, v2
	v_cvt_pk_bf16_f32 v2, v12, v5
	v_lshl_add_u64 v[4:5], s[26:27], 0, v[20:21]
	v_cvt_pk_bf16_f32 v3, v6, v3
	global_store_dwordx4 v[4:5], v[0:3], off
